# cache-warming loads also for the odd-layer W_in conversion segments
# baseline (speedup 1.0000x reference)
; DI int otid() { int z; asm volatile("s_mov_b32 %0, 0" : "=s"(z)); return (int)threadIdx.x + z; }
; DI void cvt_tile(const CvtSeg& s, int tile, char* smem) {
;   float* T = (float*)smem;
;   const int tid = otid();
;   const int nkt = s.K >> 6;
;   const int kt = tile % nkt, nt = tile / nkt;
;   const int k0 = kt * 64, n0 = nt * 64;
;   __syncthreads();
; #pragma unroll
;   for (int i = 0; i < 4; ++i) {
;     const int k = i * 16 + (tid >> 4), n4 = (tid & 15) * 4;
;     float4 v = make_float4(0.f, 0.f, 0.f, 0.f);
;     if (n0 + n4 < s.ncols) {
;       v = *(const float4*)(s.src + (size_t)(k0 + k) * s.lds + s.sc0 + n0 + n4);
.LBB0_1127:
	v_readlane_b32 s12, v255, 36
	v_readlane_b32 s13, v255, 37
	s_load_dwordx2 s[12:13], s[12:13], 0x0
	s_mov_b32 s14, 0
	v_mov_b32_e32 v4, 0
	v_add_u32_e32 v10, s14, v189
	v_readlane_b32 s14, v255, 27
	s_waitcnt lgkmcnt(0)
	s_add_u32 s24, s12, s14
	v_readlane_b32 s12, v255, 26
	s_addc_u32 s13, s13, s12
	s_ashr_i32 s12, s37, 31
	s_lshr_b32 s12, s12, 27
	s_add_i32 s12, s37, s12
	s_and_b32 s14, s12, 0x3ffffe0
	s_lshl_b32 s15, s12, 1
	s_sub_i32 s12, s37, s14
	s_and_b32 s14, s15, 0xffffffc0
	s_ashr_i32 s15, s14, 31
	s_lshl_b32 s12, s12, 6
	v_lshlrev_b32_e32 v0, 2, v10
	s_lshl_b64 s[16:17], s[14:15], 2
	v_and_b32_e32 v0, 60, v0
	s_add_u32 s16, s24, s16
	v_or_b32_e32 v2, s14, v0
	s_addc_u32 s17, s13, s17
	v_lshlrev_b32_e32 v0, 2, v0
	v_cmp_gt_i32_e32 vcc, 64, v2
	v_lshl_add_u64 v[2:3], s[16:17], 0, v[0:1]
	s_mov_b64 s[16:17], 0x1000
	v_ashrrev_i32_e32 v11, 4, v10
	v_lshl_add_u64 v[8:9], v[2:3], 0, s[16:17]
	v_mov_b32_e32 v2, 0
	v_mov_b32_e32 v5, 0
	v_mov_b32_e32 v6, 0
	v_mov_b32_e32 v7, 0
	s_barrier
	s_and_saveexec_b64 s[16:17], vcc
	s_cbranch_execz .LBB0_1129
	v_add_u32_e32 v3, s12, v11
	s_movk_i32 s13, 0x6960
	v_mad_i64_i32 v[4:5], s[24:25], v3, s13, v[8:9]
	v_mov_b32_e32 v44, 0x69600
	v_mov_b32_e32 v45, 0
	v_lshl_add_u64 v[46:47], v[4:5], 0, v[44:45]
	global_load_dwordx4 v[32:35], v[46:47], off
	v_lshl_add_u64 v[46:47], v[46:47], 0, v[44:45]
	global_load_dwordx4 v[36:39], v[46:47], off
	v_lshl_add_u64 v[46:47], v[46:47], 0, v[44:45]
	global_load_dwordx4 v[40:43], v[46:47], off
	global_load_dwordx4 v[4:7], v[4:5], off

; DI int otid() { int z; asm volatile("s_mov_b32 %0, 0" : "=s"(z)); return (int)threadIdx.x + z; }
; DI void cvt_tile(const CvtSeg& s, int tile, char* smem) {
;   float* T = (float*)smem;
;   const int tid = otid();
;   const int nkt = s.K >> 6;
;   const int kt = tile % nkt, nt = tile / nkt;
;   const int k0 = kt * 64, n0 = nt * 64;
;   __syncthreads();
; #pragma unroll
;   for (int i = 0; i < 4; ++i) {
;     const int k = i * 16 + (tid >> 4), n4 = (tid & 15) * 4;
;     float4 v = make_float4(0.f, 0.f, 0.f, 0.f);
;     if (n0 + n4 < s.ncols) {
;       v = *(const float4*)(s.src + (size_t)(k0 + k) * s.lds + s.sc0 + n0 + n4);
.LBB0_1151:
	s_andn2_b64 vcc, exec, s[12:13]
	s_cbranch_vccnz .LBB0_1138
	s_mov_b32 s12, 0
	s_lshl_b64 s[16:17], s[16:17], 2
	v_add_u32_e32 v10, s12, v189
	s_ashr_i32 s12, s36, 31
	s_lshr_b32 s12, s12, 27
	s_add_i32 s13, s36, s12
	s_and_b32 s12, s13, 0x3ffffe0
	s_sub_i32 s12, s36, s12
	s_lshl_b32 s13, s13, 1
	v_lshlrev_b32_e32 v0, 2, v10
	s_lshl_b32 s12, s12, 6
	s_and_b32 s14, s13, 0xffffffc0
	v_and_b32_e32 v0, 60, v0
	v_or_b32_e32 v2, s14, v0
	s_add_u32 s13, s37, s16
	v_cmp_gt_i32_e32 vcc, s15, v2
	s_addc_u32 s24, s46, s17
	s_ashr_i32 s15, s14, 31
	s_lshl_b64 s[16:17], s[14:15], 2
	s_add_u32 s16, s13, s16
	s_addc_u32 s17, s24, s17
	v_lshlrev_b32_e32 v0, 2, v0
	v_ashrrev_i32_e32 v11, 4, v10
	v_lshl_add_u64 v[8:9], s[16:17], 0, v[0:1]
	v_mov_b32_e32 v2, 0
	v_mov_b32_e32 v4, 0
	v_mov_b32_e32 v5, 0
	v_mov_b32_e32 v6, 0
	v_mov_b32_e32 v7, 0
	s_barrier
	s_and_saveexec_b64 s[16:17], vcc
	s_cbranch_execz .LBB0_1154
	v_add_u32_e32 v3, s12, v11
	s_movk_i32 s13, 0x6960
	v_mad_i64_i32 v[4:5], s[24:25], v3, s13, v[8:9]
	v_mov_b32_e32 v44, 0x69600
	v_mov_b32_e32 v45, 0
	v_lshl_add_u64 v[46:47], v[4:5], 0, v[44:45]
	global_load_dwordx4 v[32:35], v[46:47], off
	v_lshl_add_u64 v[46:47], v[46:47], 0, v[44:45]
	global_load_dwordx4 v[36:39], v[46:47], off
	v_lshl_add_u64 v[46:47], v[46:47], 0, v[44:45]
	global_load_dwordx4 v[40:43], v[46:47], off
	global_load_dwordx4 v[4:7], v[4:5], off
